# MLA softmax: first-tile pad masking skipped by a scalar branch on all other tiles
# speedup vs baseline: 1.0149x; 1.0149x over previous
; #define LAS __attribute__((address_space(3)))
; #define SBAR() __builtin_amdgcn_sched_barrier(0)
; template <int TYPE>
; __device__ __forceinline__ void attn_item(const Params& p, int layer, int head, int qb, int mode, LAS unsigned char* lds) {
;     ...
;         if (kbase <= w_last) {
;             f32x16 p0 = (f32x16){}, p1 = (f32x16){};
;             const LAS unsigned char* kt = K_lds + bf * SHM_K;
; #pragma unroll
;             for (int d0 = 0; d0 < NQ; ++d0) {
;                 const LAS unsigned char* a = d0 < 8 ? kt + kb[d0 & 3] + (d0 >> 2) * 128 : kt + kbr[d0 & 3];
;                 const bf16x8 b0 = *(const LAS bf16x8*)a, b1 = *(const LAS bf16x8*)(a + (d0 < 8 ? 32 * 256 : 32 * 128));
;                 p0 = __builtin_amdgcn_mfma_f32_32x32x16_bf16(b0, qr[d0], p0, 0, 0, 0);
;                 p1 = __builtin_amdgcn_mfma_f32_32x32x16_bf16(b1, qr[d0], p1, 0, 0, 0);
;                 if ((d0 & 3) == 3) SBAR();
;             }
;             if (TYPE == 1) {
;                 const LAS float* bb = B_lds + bf * 64 + 4 * hi;
; #pragma unroll
;                 for (int q4 = 0; q4 < 4; ++q4) {
;                     const f32x4 b0 = *(const LAS f32x4*)(bb + 8 * q4), b1 = *(const LAS f32x4*)(bb + 32 + 8 * q4);
; #pragma unroll
;                     for (int j = 0; j < 4; ++j) { p0[q4 * 4 + j] += b0[j]; p1[q4 * 4 + j] += b1[j]; }
;                 }
;             }
;             if (TYPE == 1 && kbase + 63 > w_first) {
;                 const int lim = my_kmax - kbase - 4 * hi; const float NEGI = -__builtin_inff();
; #pragma unroll
;                 for (int r = 0; r < 16; ++r) { const int c = (r & 3) + 8 * (r >> 2); if (c > lim) p0[r] = NEGI; if (c + 32 > lim) p1[r] = NEGI; }
;             }
;             if (t == T0) {
;                 const int lo = (PADR & 63) - 4 * hi; const float NEGI = -__builtin_inff();
; #pragma unroll
;                 for (int r = 0; r < 16; ++r) { const int c = (r & 3) + 8 * (r >> 2); if (c < lo) p0[r] = NEGI; if (c + 32 < lo) p1[r] = NEGI; }
;             }
.LBB0_821:
	s_cmp_gt_i32 s11, s10
	s_cbranch_scc1 .LBB0_818
	s_mul_i32 s19, s28, 0x6000
	s_add_i32 s19, s19, 0
	v_add_u32_e32 v102, s19, v230
	v_add_u32_e32 v103, v102, v228
	v_add_u32_e32 v104, s19, v231
	v_add_u32_e32 v105, v104, v228
	v_add_u32_e32 v106, s19, v232
	v_add_u32_e32 v107, v106, v228
	v_add_u32_e32 v108, s19, v233
	v_add_u32_e32 v109, v108, v228
	v_add_u32_e32 v248, v102, v229
	v_add_u32_e32 v249, v104, v229
	v_add_u32_e32 v250, v106, v229
	v_add_u32_e32 v251, v108, v229
	ds_read_b128 v[98:101], v103 offset:32768
	ds_read_b128 v[110:113], v103 offset:40960
	ds_read_b128 v[114:117], v105 offset:32768
	ds_read_b128 v[118:121], v105 offset:40960
	ds_read_b128 v[122:125], v107 offset:32768
	ds_read_b128 v[126:129], v107 offset:40960
	ds_read_b128 v[178:181], v109 offset:32768
	ds_read_b128 v[182:185], v109 offset:40960
	ds_read_b128 v[186:189], v103 offset:32896
	ds_read_b128 v[190:193], v103 offset:41088
	ds_read_b128 v[240:243], v105 offset:32896
	ds_read_b128 v[244:247], v105 offset:41088
	s_waitcnt lgkmcnt(11)
	v_mfma_f32_32x32x16_bf16 v[82:97], v[98:101], v[130:133], 0
	ds_read_b128 v[98:101], v107 offset:32896
	s_waitcnt lgkmcnt(11)
	v_mfma_f32_32x32x16_bf16 v[66:81], v[110:113], v[130:133], 0
	ds_read_b128 v[110:113], v107 offset:41088
	s_waitcnt lgkmcnt(11)
	v_mfma_f32_32x32x16_bf16 v[82:97], v[114:117], v[134:137], v[82:97]
	ds_read_b128 v[114:117], v109 offset:32896
	s_waitcnt lgkmcnt(11)
	v_mfma_f32_32x32x16_bf16 v[66:81], v[118:121], v[134:137], v[66:81]
	ds_read_b128 v[118:121], v109 offset:41088
	s_waitcnt lgkmcnt(11)
	v_mfma_f32_32x32x16_bf16 v[82:97], v[122:125], v[138:141], v[82:97]
	ds_read_b128 v[122:125], v248 offset:49152
	s_waitcnt lgkmcnt(11)
	v_mfma_f32_32x32x16_bf16 v[66:81], v[126:129], v[138:141], v[66:81]
	ds_read_b128 v[126:129], v248 offset:53248
	s_waitcnt lgkmcnt(11)
	v_mfma_f32_32x32x16_bf16 v[82:97], v[178:181], v[142:145], v[82:97]
	ds_read_b128 v[178:181], v249 offset:49152
	s_waitcnt lgkmcnt(11)
	v_mfma_f32_32x32x16_bf16 v[66:81], v[182:185], v[142:145], v[66:81]
	ds_read_b128 v[182:185], v249 offset:53248
	s_waitcnt lgkmcnt(11)
	v_mfma_f32_32x32x16_bf16 v[82:97], v[186:189], v[146:149], v[82:97]
	ds_read_b128 v[186:189], v250 offset:49152
	s_waitcnt lgkmcnt(11)
	v_mfma_f32_32x32x16_bf16 v[66:81], v[190:193], v[146:149], v[66:81]
	ds_read_b128 v[190:193], v250 offset:53248
	s_waitcnt lgkmcnt(11)
	v_mfma_f32_32x32x16_bf16 v[82:97], v[240:243], v[150:153], v[82:97]
	ds_read_b128 v[240:243], v251 offset:49152
	s_waitcnt lgkmcnt(11)
	v_mfma_f32_32x32x16_bf16 v[66:81], v[244:247], v[150:153], v[66:81]
	ds_read_b128 v[244:247], v251 offset:53248
	s_waitcnt lgkmcnt(11)
	v_mfma_f32_32x32x16_bf16 v[82:97], v[98:101], v[154:157], v[82:97]
	s_waitcnt lgkmcnt(10)
	v_mfma_f32_32x32x16_bf16 v[66:81], v[110:113], v[154:157], v[66:81]
	s_waitcnt lgkmcnt(9)
	v_mfma_f32_32x32x16_bf16 v[82:97], v[114:117], v[158:161], v[82:97]
	s_waitcnt lgkmcnt(8)
	v_mfma_f32_32x32x16_bf16 v[66:81], v[118:121], v[158:161], v[66:81]
	s_waitcnt lgkmcnt(7)
	v_mfma_f32_32x32x16_bf16 v[82:97], v[122:125], v[162:165], v[82:97]
	s_waitcnt lgkmcnt(6)
	v_mfma_f32_32x32x16_bf16 v[66:81], v[126:129], v[162:165], v[66:81]
	s_waitcnt lgkmcnt(5)
	v_mfma_f32_32x32x16_bf16 v[82:97], v[178:181], v[166:169], v[82:97]
	s_waitcnt lgkmcnt(4)
	v_mfma_f32_32x32x16_bf16 v[66:81], v[182:185], v[166:169], v[66:81]
	s_waitcnt lgkmcnt(3)
	v_mfma_f32_32x32x16_bf16 v[82:97], v[186:189], v[170:173], v[82:97]
	s_waitcnt lgkmcnt(2)
	v_mfma_f32_32x32x16_bf16 v[66:81], v[190:193], v[170:173], v[66:81]
	s_waitcnt lgkmcnt(1)
	v_mfma_f32_32x32x16_bf16 v[82:97], v[240:243], v[174:177], v[82:97]
	s_waitcnt lgkmcnt(0)
	v_mfma_f32_32x32x16_bf16 v[66:81], v[244:247], v[174:177], v[66:81]
	s_cmp_eq_u32 s18, 3
	s_cselect_b64 vcc, -1, 0
	s_nop 7
	s_cbranch_scc0 .Lmla_nomask
	v_cndmask_b32_e32 v82, v82, v219, vcc
	v_cndmask_b32_e32 v83, v83, v219, vcc
	v_cndmask_b32_e32 v85, v85, v219, vcc
	v_cndmask_b32_e32 v84, v84, v219, vcc
	v_cndmask_b32_e32 v87, v87, v219, vcc
	v_cndmask_b32_e32 v86, v86, v219, vcc
	v_cndmask_b32_e32 v89, v89, v219, vcc
	v_cndmask_b32_e32 v88, v88, v219, vcc
	v_cndmask_b32_e32 v91, v91, v219, vcc
	v_cndmask_b32_e32 v90, v90, v219, vcc
	v_cndmask_b32_e32 v93, v93, v219, vcc
	v_cndmask_b32_e32 v92, v92, v219, vcc
	v_cndmask_b32_e32 v95, v95, v219, vcc
	v_cndmask_b32_e32 v94, v94, v219, vcc
	v_cndmask_b32_e32 v97, v97, v219, vcc
	v_cndmask_b32_e32 v96, v96, v219, vcc
	v_cndmask_b32_e32 v67, v67, v219, vcc
	v_cndmask_b32_e32 v66, v66, v219, vcc
	v_cndmask_b32_e32 v69, v69, v219, vcc
	v_cndmask_b32_e32 v68, v68, v219, vcc
	v_cndmask_b32_e32 v71, v71, v219, vcc
	v_cndmask_b32_e32 v70, v70, v219, vcc
	v_cndmask_b32_e32 v73, v73, v219, vcc
	v_cndmask_b32_e32 v72, v72, v219, vcc
; __device__ __forceinline__ int crow(int r, int hi) { return (r & 3) + 8 * (r >> 2) + 4 * hi; }
; template <int TYPE>
; __device__ __forceinline__ void attn_item(const Params& p, int layer, int head, int qb, int mode, LAS unsigned char* lds) {
;     ...
;             float pmax = p0[0];
; #pragma unroll
;             for (int r = 1; r < 16; ++r) pmax = fmaxf(pmax, p0[r]);
; #pragma unroll
;             for (int r = 0; r < 16; ++r) pmax = fmaxf(pmax, p1[r]);
;             { auto rr = __builtin_amdgcn_permlane32_swap(__float_as_uint(pmax), __float_as_uint(pmax), false, false);
;               pmax = fmaxf(__uint_as_float(rr[0]), __uint_as_float(rr[1])); }
;             float mn, alpha;
;             if (__all((pmax - m_reg) <= (TYPE == 1 ? 2.0f : 11.5f))) { mn = m_reg; alpha = 1.f; }
;             else { mn = fmaxf(m_reg, pmax); alpha = __builtin_amdgcn_exp2f(m_reg - mn); m_reg = mn; }
;             float ps = 0.f;
; #pragma unroll
;             for (int r = 0; r < 16; ++r) { p0[r] = __builtin_amdgcn_exp2f(p0[r] - mn); p1[r] = __builtin_amdgcn_exp2f(p1[r] - mn); ps += p0[r] + p1[r]; }
;             { auto rr = __builtin_amdgcn_permlane32_swap(__float_as_uint(ps), __float_as_uint(ps), false, false);
;               ps = __uint_as_float(rr[0]) + __uint_as_float(rr[1]); }
;             l_reg = l_reg * alpha + ps;
;             bf16x8 pa0, pa1, pa2, pa3;
;     ...
;             PK4(p0, 0, pa0); PK4(p0, 8, pa1); PK4(p1, 0, pa2); PK4(p1, 8, pa3);
;     ...
;             if (__any(alpha < 1.f)) {
;                 if (hi == 0) wsl[r32] = alpha;
;                 asm volatile("s_waitcnt lgkmcnt(0)" ::: "memory");
; #pragma unroll
;                 for (int r = 0; r < 16; ++r) { const float al = wsl[crow(r, hi)];
; #pragma unroll
;                     for (int d = 0; d < 4; ++d) o[d][r] *= al; }
.Lmla_nomask:
	v_max_f32_e32 v98, v83, v83
	v_max_f32_e32 v99, v82, v82
	v_max_f32_e32 v98, v99, v98
	v_max3_f32 v98, v98, v84, v85
	v_max3_f32 v98, v98, v86, v87
	v_max3_f32 v98, v98, v88, v89
	v_max3_f32 v98, v98, v90, v91
	v_max3_f32 v98, v98, v92, v93
	v_max3_f32 v98, v98, v94, v95
	v_max3_f32 v98, v98, v96, v97
	v_max3_f32 v98, v98, v66, v67
	v_max3_f32 v98, v98, v68, v69
	v_max3_f32 v98, v98, v70, v71
	v_max3_f32 v98, v98, v72, v73
	v_max3_f32 v98, v98, v74, v75
	v_max3_f32 v98, v98, v76, v77
	v_max3_f32 v98, v98, v78, v79
	v_max3_f32 v98, v98, v80, v81
	v_mov_b32_e32 v99, v98
	s_nop 1
	v_permlane32_swap_b32_e32 v98, v99
	v_max_f32_e32 v99, v99, v99
	v_max_f32_e32 v98, v98, v98
	v_max_f32_e32 v98, v98, v99
	v_sub_f32_e32 v99, v98, v198
	s_mov_b32 s18, 0x41380000
	v_cmp_ge_f32_e32 vcc, s18, v99
	s_cmp_eq_u64 vcc, exec
	v_max_f32_e32 v99, v198, v198
	v_max_f32_e32 v98, v99, v98
	s_cselect_b64 vcc, -1, 0
	v_sub_f32_e32 v99, v198, v98
	v_cndmask_b32_e32 v198, v98, v198, vcc
	v_sub_f32_e32 v82, v82, v198
	v_sub_f32_e32 v66, v66, v198
	v_exp_f32_e32 v82, v82
	v_exp_f32_e32 v66, v66
	v_sub_f32_e32 v83, v83, v198
	v_sub_f32_e32 v67, v67, v198
	v_exp_f32_e32 v83, v83
	v_exp_f32_e32 v67, v67
	v_sub_f32_e32 v84, v84, v198
	v_sub_f32_e32 v68, v68, v198
	v_exp_f32_e32 v84, v84
	v_exp_f32_e32 v68, v68
	v_sub_f32_e32 v85, v85, v198
	v_sub_f32_e32 v69, v69, v198
	v_exp_f32_e32 v85, v85
	v_exp_f32_e32 v69, v69
	v_sub_f32_e32 v86, v86, v198
	v_sub_f32_e32 v70, v70, v198
	v_exp_f32_e32 v98, v99
	v_add_f32_e32 v99, v66, v82
	v_exp_f32_e32 v86, v86
	v_exp_f32_e32 v70, v70
	v_sub_f32_e32 v87, v87, v198
	v_sub_f32_e32 v71, v71, v198
	v_add_f32_e32 v99, 0, v99
	v_add_f32_e32 v100, v67, v83
	v_exp_f32_e32 v87, v87
	v_exp_f32_e32 v71, v71
	v_sub_f32_e32 v88, v88, v198
	v_sub_f32_e32 v72, v72, v198
	v_add_f32_e32 v99, v100, v99
	v_add_f32_e32 v100, v68, v84
	v_exp_f32_e32 v88, v88
	v_exp_f32_e32 v72, v72
	v_sub_f32_e32 v89, v89, v198
	v_sub_f32_e32 v73, v73, v198
	v_add_f32_e32 v99, v100, v99
	v_add_f32_e32 v100, v69, v85
	v_exp_f32_e32 v89, v89
	v_exp_f32_e32 v73, v73
	v_sub_f32_e32 v90, v90, v198
	v_sub_f32_e32 v74, v74, v198
	v_add_f32_e32 v99, v100, v99
	v_add_f32_e32 v100, v70, v86
	v_exp_f32_e32 v90, v90
	v_exp_f32_e32 v74, v74
	v_sub_f32_e32 v91, v91, v198
	v_sub_f32_e32 v75, v75, v198
	v_add_f32_e32 v99, v100, v99
	v_add_f32_e32 v100, v71, v87
	v_exp_f32_e32 v91, v91
	v_exp_f32_e32 v75, v75
	v_sub_f32_e32 v92, v92, v198
	v_sub_f32_e32 v76, v76, v198
	v_add_f32_e32 v99, v100, v99
	v_add_f32_e32 v100, v72, v88
	v_exp_f32_e32 v92, v92
	v_exp_f32_e32 v76, v76
	v_sub_f32_e32 v93, v93, v198
	v_sub_f32_e32 v77, v77, v198
	v_add_f32_e32 v99, v100, v99
	v_add_f32_e32 v100, v73, v89
	v_exp_f32_e32 v93, v93
	v_exp_f32_e32 v77, v77
	v_sub_f32_e32 v94, v94, v198
	v_sub_f32_e32 v78, v78, v198
	v_add_f32_e32 v99, v100, v99
	v_add_f32_e32 v100, v74, v90
	v_exp_f32_e32 v94, v94
	v_exp_f32_e32 v78, v78
	v_sub_f32_e32 v95, v95, v198
	v_sub_f32_e32 v79, v79, v198
	v_add_f32_e32 v99, v100, v99
	v_add_f32_e32 v100, v75, v91
	v_exp_f32_e32 v95, v95
	v_exp_f32_e32 v79, v79
	v_sub_f32_e32 v96, v96, v198
	v_sub_f32_e32 v80, v80, v198
	v_add_f32_e32 v99, v100, v99
	v_add_f32_e32 v100, v76, v92
	v_exp_f32_e32 v96, v96
	v_exp_f32_e32 v80, v80
	v_sub_f32_e32 v97, v97, v198
	v_sub_f32_e32 v81, v81, v198
	v_add_f32_e32 v99, v100, v99
	v_add_f32_e32 v100, v77, v93
	v_exp_f32_e32 v97, v97
	v_exp_f32_e32 v81, v81
	v_add_f32_e32 v99, v100, v99
	v_add_f32_e32 v100, v78, v94
	v_add_f32_e32 v99, v100, v99
	v_add_f32_e32 v100, v79, v95
	v_add_f32_e32 v99, v100, v99
	v_add_f32_e32 v100, v80, v96
	v_add_f32_e32 v99, v100, v99
	v_add_f32_e32 v100, v81, v97
	v_add_f32_e32 v237, v100, v99
	v_cndmask_b32_e64 v236, v98, 1.0, vcc
	v_mov_b32_e32 v238, v237
	v_cvt_pk_bf16_f32 v178, v82, v83
	v_cvt_pk_bf16_f32 v179, v84, v85
	v_cvt_pk_bf16_f32 v180, v86, v87
	v_cvt_pk_bf16_f32 v181, v88, v89
	v_cvt_pk_bf16_f32 v182, v90, v91
	v_cvt_pk_bf16_f32 v183, v92, v93
	v_cvt_pk_bf16_f32 v184, v94, v95
	v_cvt_pk_bf16_f32 v185, v96, v97
	v_cvt_pk_bf16_f32 v186, v66, v67
	v_cvt_pk_bf16_f32 v187, v68, v69
	v_cvt_pk_bf16_f32 v188, v70, v71
	v_cvt_pk_bf16_f32 v189, v72, v73
	v_cvt_pk_bf16_f32 v190, v74, v75
	v_cvt_pk_bf16_f32 v191, v76, v77
	v_cvt_pk_bf16_f32 v192, v78, v79
	v_cvt_pk_bf16_f32 v193, v80, v81
	s_nop 1
	v_permlane32_swap_b32_e32 v237, v238
	v_permlane32_swap_b32_e32 v178, v180
	v_permlane32_swap_b32_e32 v179, v181
	v_permlane32_swap_b32_e32 v182, v184
	v_permlane32_swap_b32_e32 v183, v185
	v_permlane32_swap_b32_e32 v186, v188
	v_permlane32_swap_b32_e32 v187, v189
	v_permlane32_swap_b32_e32 v190, v192
	v_permlane32_swap_b32_e32 v191, v193
	v_cmp_gt_f32_e32 vcc, 1.0, v236
	s_cbranch_vccz .LBB0_826
	s_and_saveexec_b64 s[40:41], s[0:1]
	ds_write_b32 v235, v236
	s_or_b64 exec, exec, s[40:41]
	s_waitcnt lgkmcnt(0)
	ds_read_b128 v[66:69], v0 offset:96
	ds_read_b128 v[70:73], v0 offset:64
	ds_read_b128 v[74:77], v0 offset:32
	ds_read_b128 v[78:81], v0
	s_waitcnt lgkmcnt(0)
	v_pk_mul_f32 v[14:15], v[14:15], v[66:67]
	v_pk_mul_f32 v[10:11], v[10:11], v[70:71]
	v_pk_mul_f32 v[6:7], v[6:7], v[74:75]
	v_pk_mul_f32 v[16:17], v[16:17], v[68:69]
	v_pk_mul_f32 v[12:13], v[12:13], v[72:73]
	v_pk_mul_f32 v[8:9], v[8:9], v[76:77]
	v_pk_mul_f32 v[4:5], v[4:5], v[80:81]
	v_pk_mul_f32 v[2:3], v[2:3], v[78:79]
	v_pk_mul_f32 v[62:63], v[62:63], v[66:67]
	v_pk_mul_f32 v[58:59], v[58:59], v[70:71]
	v_pk_mul_f32 v[54:55], v[54:55], v[74:75]
	v_pk_mul_f32 v[64:65], v[64:65], v[68:69]
	v_pk_mul_f32 v[60:61], v[60:61], v[72:73]
	v_pk_mul_f32 v[56:57], v[56:57], v[76:77]
	v_pk_mul_f32 v[52:53], v[52:53], v[80:81]
	v_pk_mul_f32 v[50:51], v[50:51], v[78:79]
	v_pk_mul_f32 v[46:47], v[46:47], v[66:67]
	v_pk_mul_f32 v[42:43], v[42:43], v[70:71]
	v_pk_mul_f32 v[38:39], v[38:39], v[74:75]
	v_pk_mul_f32 v[48:49], v[48:49], v[68:69]
	v_pk_mul_f32 v[44:45], v[44:45], v[72:73]
	v_pk_mul_f32 v[40:41], v[40:41], v[76:77]
	v_pk_mul_f32 v[36:37], v[36:37], v[80:81]
	v_pk_mul_f32 v[34:35], v[34:35], v[78:79]
	v_pk_mul_f32 v[30:31], v[30:31], v[66:67]
	v_pk_mul_f32 v[26:27], v[26:27], v[70:71]
	v_pk_mul_f32 v[22:23], v[22:23], v[74:75]
	v_pk_mul_f32 v[32:33], v[32:33], v[68:69]
	v_pk_mul_f32 v[28:29], v[28:29], v[72:73]
	v_pk_mul_f32 v[24:25], v[24:25], v[76:77]
	v_pk_mul_f32 v[20:21], v[20:21], v[80:81]
	v_pk_mul_f32 v[18:19], v[18:19], v[78:79]
